# cross-XCD UP pass sharing with 21 helper workgroups (3 per remote XCD)
# baseline (speedup 1.0000x reference)
; DI const bf16_t* wp(const Params& p, int l, size_t off) { return (const bf16_t*)(p.ws + OFF_WP) + (size_t)l * PW_LAYER + off; }
; template <int MT> DI void phaseB(const Params& p, int l, int t, unsigned char* lds) {
;     ...
;     EpiUp<MT> eu; eu.priv = priv; eu.d2 = d2;
;     eu.halo = (float*)(ws + OFF_UHALO) + (size_t)t * 2 * DFF2;
;     eu.pconv = t == NTILE - 1 ? p.out + O_PCONV + (size_t)l * 2 * DFF2 : nullptr;
;     eu.sconv = p.out + O_SCONV + ((size_t)l * 8 + 2 * t) * 2 * DFF2;
;     gemm64<1024, MT>(xb, DM, d2, wp(p, l, PW_UP), DFF2 / UW, lds, eu);
.LBB0_705:
	v_readlane_b32 s0, v254, 57
	s_nop 3
	s_cmp_lt_u32 s0, 4
	s_cbranch_scc1 .Lhu_done
	s_and_b32 s0, s0, 31
	s_cmp_gt_u32 s0, 2
	s_cbranch_scc1 .Lhu_done
	v_writelane_b32 v180, s0, 0
	v_writelane_b32 v180, s1, 1
	v_writelane_b32 v180, s2, 2
	v_writelane_b32 v180, s3, 3
	v_writelane_b32 v180, s4, 4
	v_writelane_b32 v180, s5, 5
	v_writelane_b32 v180, s6, 6
	v_writelane_b32 v180, s7, 7
	v_writelane_b32 v180, s8, 8
	v_writelane_b32 v180, s9, 9
	v_writelane_b32 v180, s10, 10
	v_writelane_b32 v180, s11, 11
	v_writelane_b32 v180, s12, 12
	v_writelane_b32 v180, s13, 13
	v_writelane_b32 v180, s14, 14
	v_writelane_b32 v180, s15, 15
	v_writelane_b32 v180, s16, 16
	v_writelane_b32 v180, s17, 17
	v_writelane_b32 v180, s18, 18
	v_writelane_b32 v180, s19, 19
	v_writelane_b32 v180, s20, 20
	v_writelane_b32 v180, s21, 21
	v_writelane_b32 v180, s22, 22
	v_writelane_b32 v180, s23, 23
	v_writelane_b32 v180, s24, 24
	v_writelane_b32 v180, s25, 25
	v_writelane_b32 v180, s26, 26
	v_writelane_b32 v180, s27, 27
	v_writelane_b32 v180, s28, 28
	v_writelane_b32 v180, s29, 29
	v_writelane_b32 v180, s30, 30
	v_writelane_b32 v180, s31, 31
	v_writelane_b32 v180, s32, 32
	v_writelane_b32 v180, s33, 33
	v_writelane_b32 v180, s34, 34
	v_writelane_b32 v180, s35, 35
	v_writelane_b32 v180, s36, 36
	v_writelane_b32 v180, s37, 37
	v_writelane_b32 v180, s38, 38
	v_writelane_b32 v180, s39, 39
	v_writelane_b32 v180, s40, 40
	v_writelane_b32 v180, s41, 41
	v_writelane_b32 v180, s42, 42
	v_writelane_b32 v180, s43, 43
	v_writelane_b32 v180, s44, 44
	v_writelane_b32 v180, s45, 45
	v_writelane_b32 v180, s46, 46
	v_writelane_b32 v180, s47, 47
	v_writelane_b32 v180, s48, 48
	v_writelane_b32 v180, s49, 49
	v_writelane_b32 v180, s50, 50
	v_writelane_b32 v180, s51, 51
	v_writelane_b32 v180, s52, 52
	v_writelane_b32 v180, s53, 53
	v_writelane_b32 v180, s54, 54
	v_writelane_b32 v180, s55, 55
	v_writelane_b32 v180, s56, 56
	v_writelane_b32 v180, s57, 57
	v_writelane_b32 v180, s58, 58
	v_writelane_b32 v180, s59, 59
	v_writelane_b32 v180, s60, 60
	v_writelane_b32 v180, s61, 61
	v_writelane_b32 v180, s62, 62
	v_writelane_b32 v180, s63, 63
	v_writelane_b32 v181, s64, 0
	v_writelane_b32 v181, s65, 1
	v_writelane_b32 v181, s66, 2
	v_writelane_b32 v181, s67, 3
	v_writelane_b32 v181, s68, 4
	v_writelane_b32 v181, s69, 5
	v_writelane_b32 v181, s70, 6
	v_writelane_b32 v181, s71, 7
	v_writelane_b32 v181, s72, 8
	v_writelane_b32 v181, s73, 9
	v_writelane_b32 v181, s74, 10
	v_writelane_b32 v181, s75, 11
	v_writelane_b32 v181, s76, 12
	v_writelane_b32 v181, s77, 13
	v_writelane_b32 v181, s78, 14
	v_writelane_b32 v181, s79, 15
	v_writelane_b32 v181, s80, 16
	v_writelane_b32 v181, s81, 17
	v_writelane_b32 v181, s82, 18
	v_writelane_b32 v181, s83, 19
	v_writelane_b32 v181, s84, 20
	v_writelane_b32 v181, s85, 21
	v_writelane_b32 v181, s86, 22
	v_writelane_b32 v181, s87, 23
	v_writelane_b32 v181, s88, 24
	v_writelane_b32 v181, s89, 25
	v_writelane_b32 v181, s90, 26
	v_writelane_b32 v181, s91, 27
	v_writelane_b32 v181, s92, 28
	v_writelane_b32 v181, s93, 29
	v_writelane_b32 v181, s94, 30
	v_writelane_b32 v181, s95, 31
	v_writelane_b32 v181, s96, 32
	v_writelane_b32 v181, s97, 33
	v_writelane_b32 v181, s98, 34
	v_writelane_b32 v181, s99, 35
	v_writelane_b32 v181, s100, 36
	v_writelane_b32 v181, s101, 37
	v_writelane_b32 v181, vcc_lo, 38
	v_writelane_b32 v181, vcc_hi, 39
	s_getreg_b32 s70, hwreg(HW_REG_XCC_ID, 0, 4)
	s_mov_b32 s43, 0xb0000
	s_movk_i32 s44, 0x1600
	s_mov_b32 s65, 0
	v_readlane_b32 s66, v252, 10
	v_readlane_b32 s67, v252, 11
	v_readlane_b32 s68, v254, 57
	s_mov_b32 s69, 0
	s_mov_b32 s80, 0
	v_lshrrev_b32_e32 v223, 6, v176
